# static priority raise (s_setprio 1) for workgroups with index >= 256 during the phase 2 and phase 6 GEMM task loops
# speedup vs baseline: 1.0353x; 1.0032x over previous
; DI void phase2(const Params& p, int l, unsigned char* smem) {
;   const u16* H = (const u16*)(p.ws + W_H);
;   const u16* WinT = (const u16*)(p.ws + W_WINT);
;   float* PR = (float*)(p.ws + W_PR);
;   u16* Z = (u16*)(p.ws + W_Z);
;   float* CQ = (float*)(p.ws + W_CQ); float* CKV = (float*)(p.ws + W_CKV); float* KR = (float*)(p.ws + W_KR);
;   u16* SQ = (u16*)(p.ws + W_SQ); u16* SBK = (u16*)(p.ws + W_SBK); u16* SBVT = (u16*)(p.ws + W_SBVT);
;   float* out = p.out;
;   for (int ts = blockIdx.x; ts < 11 * 512; ts += gridDim.x) {
.LBB0_246:
	s_movk_i32 s51, 0x300
	s_or_b64 exec, exec, s[2:3]
	v_readlane_b32 s4, v254, 4
	s_mov_b32 s2, s28
	v_readlane_b32 s5, v254, 5
	s_barrier
	s_load_dwordx2 s[4:5], s[4:5], 0x0
	s_add_u32 s84, s76, 0x4b0b700
	s_addc_u32 s85, s77, 0
	s_waitcnt lgkmcnt(0)
	v_writelane_b32 v254, s4, 37
	s_nop 1
	v_writelane_b32 v254, s5, 38
	s_add_u32 s4, s76, 0xb3db700
	s_addc_u32 s5, s77, 0
	v_writelane_b32 v254, s4, 39
	s_nop 1
	v_writelane_b32 v254, s5, 40
	s_add_u32 s4, s76, 0xe43b700
	s_addc_u32 s5, s77, 0
	s_add_u32 s36, s76, 0xfc6b700
	s_addc_u32 s37, s77, 0
	s_add_u32 s38, s76, 0x10c8b700
	v_writelane_b32 v254, s4, 41
	s_addc_u32 s39, s77, 0
	s_nop 0
	v_writelane_b32 v254, s5, 42
	s_add_u32 s4, s76, 0x12abf700
	s_addc_u32 s5, s77, 0
	v_writelane_b32 v254, s4, 43
	s_nop 1
	v_writelane_b32 v254, s5, 44
	s_add_u32 s4, s76, 0x13adf700
	s_addc_u32 s5, s77, 0
	v_writelane_b32 v254, s4, 45
	s_nop 1
	v_writelane_b32 v254, s5, 46
	s_add_u32 s4, s76, 0x15b0f700
	s_addc_u32 s5, s77, 0
	v_writelane_b32 v254, s4, 47
	s_nop 1
	v_writelane_b32 v254, s5, 48
	s_nop 0
	v_readlane_b32 s4, v254, 6
	v_readlane_b32 s5, v254, 7
	s_andn2_b64 vcc, exec, s[4:5]
	s_cbranch_vccnz .LBB0_444
	s_ashr_i32 s3, s2, 31
	s_lshl_b64 s[40:41], s[2:3], 16
	s_lshl_b64 s[4:5], s[2:3], 23
	s_add_u32 s42, s4, 0x4263400
	s_addc_u32 s43, s5, 0
	s_add_u32 s52, s4, 0x2263400
	s_addc_u32 s53, s5, 0
	s_lshl_b32 s80, s2, 3
	s_lshl_b32 s81, s2, 1
	s_add_u32 s86, s76, 0x2acb800
	s_addc_u32 s87, s77, 0
	s_add_u32 s90, s76, 0x100
	s_addc_u32 s91, s77, 0
	v_readlane_b32 s92, v254, 0
	s_nop 3
	s_cmpk_lt_u32 s92, 0x100
	s_cbranch_scc1 .Lprio2_skip
	s_setprio 1
.Lprio2_skip:
	s_branch .LBB0_250

; DI int TIDX() { int t = __builtin_amdgcn_workitem_id_x(); asm volatile("" : "+v"(t)); return t; }
; DI unsigned xb_ld(unsigned* q) { return __hip_atomic_load(q, __ATOMIC_RELAXED, __HIP_MEMORY_SCOPE_AGENT); }
; DI unsigned xb_add(unsigned* q, unsigned v) { return __hip_atomic_fetch_add(q, v, __ATOMIC_RELAXED, __HIP_MEMORY_SCOPE_AGENT); }
; DI unsigned xb_xcc_id() { return (unsigned)__builtin_amdgcn_s_getreg((3 << 11) | 20) & 0xFu; }
; #define XB_SPIN(cond, bar) do { unsigned _sp = 0; while (cond) { __builtin_amdgcn_s_sleep(1); \
;     if ((++_sp & 255u) == 0u) { if (xb_ld(&(bar)[XB_TMO])) break; if (_sp > XB_SPIN_CAP) { atomicAdd(&(bar)[XB_TMO], 1u); break; } } } } while (0)
; DI void xbar(const Params& p, unsigned* xbst) {
;   asm volatile("s_waitcnt vmcnt(0)" ::: "memory");
;   __syncthreads();
;   if (TIDX() == 0) {
;     unsigned* bar = (unsigned*)(p.ws + W_XBAR);
;     const unsigned x = xb_xcc_id();
;     __builtin_amdgcn_s_waitcnt(0);
;     const unsigned nloc = xbst[0], nx = xbst[1];
;     const unsigned old = xb_add(&bar[XB_XSUB(x)], 1u);
;     const unsigned gen = old / nloc;
;     if (old + 1u == (gen + 1u) * nloc) {
;       __builtin_amdgcn_fence(__ATOMIC_RELEASE, "agent");
;       asm volatile("s_waitcnt vmcnt(0)" ::: "memory");
;       const unsigned og = xb_add(&bar[XB_TOP], 1u);
;       const unsigned tg = og / nx;
;       if (og + 1u == (tg + 1u) * nx) xb_add(&bar[XB_TOPGEN], 1u);
;       else XB_SPIN(xb_ld(&bar[XB_TOPGEN]) == tg, bar);
;       __builtin_amdgcn_fence(__ATOMIC_ACQUIRE, "agent");
;       xb_add(&bar[XB_XGEN(x)], 1u);
;       asm volatile("s_waitcnt vmcnt(0)" ::: "memory");
;     } else {
;       XB_SPIN(xb_ld(&bar[XB_XGEN(x)]) == gen, bar);
.LBB0_444:
	s_setprio 0
	s_waitcnt vmcnt(0)
	s_nop 5
	v_mov_b32_e32 v0, v160
	s_waitcnt vmcnt(63) expcnt(7) lgkmcnt(15)
	s_barrier
	s_nop 0
	v_cmp_eq_u32_e32 vcc, 0, v0
	s_and_saveexec_b64 s[2:3], vcc
	s_cbranch_execz .LBB0_481
	s_getreg_b32 s4, hwreg(HW_REG_XCC_ID, 0, 4)
	v_mov_b32_e32 v0, 0x12100
	s_lshl_b32 s4, s4, 8
	s_waitcnt vmcnt(0) expcnt(0) lgkmcnt(0)
	ds_read_b64 v[0:1], v0
	s_and_b32 s4, s4, 0xf00
	s_mov_b64 s[6:7], exec
	s_add_u32 s4, s76, s4
	s_addc_u32 s5, s77, 0
	v_mbcnt_lo_u32_b32 v2, s6, 0
	s_add_u32 s4, s4, 0x2ac8100
	v_mbcnt_hi_u32_b32 v2, s7, v2
	s_addc_u32 s5, s5, 0
	v_cmp_eq_u32_e32 vcc, 0, v2
	s_and_saveexec_b64 s[8:9], vcc
	s_cbranch_execz .LBB0_447
	s_bcnt1_i32_b64 s6, s[6:7]
	v_mov_b32_e32 v3, s6
	v_mov_b32_e32 v4, 0x1000
	global_atomic_add v3, v4, v3, s[4:5] offset:1024 sc0

; DI void phase6(const Params& p, int l, unsigned char* smem) {
;   const u16* H = (const u16*)(p.ws + W_H); const u16* WinT = (const u16*)(p.ws + W_WINT);
;   const u16* YG = (const u16*)(p.ws + W_YG); u16* MG = (u16*)(p.ws + W_MG);
;   for (int t0 = blockIdx.x; t0 < 32 + 128 * 8; t0 += gridDim.x) {
.LBB0_940:
	s_or_b64 exec, exec, s[2:3]
	v_readlane_b32 s4, v254, 11
	v_readlane_b32 s5, v254, 12
	v_readlane_b32 s2, v254, 49
	s_andn2_b64 vcc, exec, s[4:5]
	s_barrier
	s_cbranch_vccnz .LBB0_960
	s_add_u32 s11, s76, 0x1090000
	s_addc_u32 s22, s77, 0
	s_add_u32 s24, s76, 0x4b0b800
	s_addc_u32 s25, s77, 0
	s_add_u32 s26, s76, 0x1090100
	s_addc_u32 s27, s77, 0
	s_add_u32 s28, s76, 0x2acb800
	s_addc_u32 s29, s77, 0
	s_add_u32 s30, s76, 0x100
	s_addc_u32 s31, s77, 0
	s_add_u32 s4, s76, 0x1090080
	s_addc_u32 s5, s77, 0
	s_add_u32 s6, s76, 0x5b0b780
	s_addc_u32 s7, s77, 0
	s_mul_i32 s23, s2, 3
	s_add_u32 s8, s76, 0x4acb780
	v_readlane_b32 s2, v254, 13
	s_addc_u32 s9, s77, 0
	v_readlane_b32 s34, v254, 14
	s_mov_b32 s10, s2
	v_readlane_b32 s35, v254, 19
	v_readlane_b32 s36, v254, 0
	s_nop 3
	s_cmpk_lt_u32 s36, 0x100
	s_cbranch_scc1 .Lprio6_skip
	s_setprio 1

; DI int TIDX() { int t = __builtin_amdgcn_workitem_id_x(); asm volatile("" : "+v"(t)); return t; }
; DI unsigned xb_ld(unsigned* q) { return __hip_atomic_load(q, __ATOMIC_RELAXED, __HIP_MEMORY_SCOPE_AGENT); }
; DI unsigned xb_add(unsigned* q, unsigned v) { return __hip_atomic_fetch_add(q, v, __ATOMIC_RELAXED, __HIP_MEMORY_SCOPE_AGENT); }
; DI unsigned xb_xcc_id() { return (unsigned)__builtin_amdgcn_s_getreg((3 << 11) | 20) & 0xFu; }
; #define XB_SPIN(cond, bar) do { unsigned _sp = 0; while (cond) { __builtin_amdgcn_s_sleep(1); \
;     if ((++_sp & 255u) == 0u) { if (xb_ld(&(bar)[XB_TMO])) break; if (_sp > XB_SPIN_CAP) { atomicAdd(&(bar)[XB_TMO], 1u); break; } } } } while (0)
; DI void xbar(const Params& p, unsigned* xbst) {
;   asm volatile("s_waitcnt vmcnt(0)" ::: "memory");
;   __syncthreads();
;   if (TIDX() == 0) {
;     unsigned* bar = (unsigned*)(p.ws + W_XBAR);
;     const unsigned x = xb_xcc_id();
;     __builtin_amdgcn_s_waitcnt(0);
;     const unsigned nloc = xbst[0], nx = xbst[1];
;     const unsigned old = xb_add(&bar[XB_XSUB(x)], 1u);
;     const unsigned gen = old / nloc;
;     if (old + 1u == (gen + 1u) * nloc) {
;       __builtin_amdgcn_fence(__ATOMIC_RELEASE, "agent");
;       asm volatile("s_waitcnt vmcnt(0)" ::: "memory");
;       const unsigned og = xb_add(&bar[XB_TOP], 1u);
;       const unsigned tg = og / nx;
;       if (og + 1u == (tg + 1u) * nx) xb_add(&bar[XB_TOPGEN], 1u);
;       else XB_SPIN(xb_ld(&bar[XB_TOPGEN]) == tg, bar);
;       __builtin_amdgcn_fence(__ATOMIC_ACQUIRE, "agent");
;       xb_add(&bar[XB_XGEN(x)], 1u);
;       asm volatile("s_waitcnt vmcnt(0)" ::: "memory");
;     } else {
;       XB_SPIN(xb_ld(&bar[XB_XGEN(x)]) == gen, bar);
.LBB0_960:
	s_setprio 0
	s_waitcnt vmcnt(0)
	v_mov_b32_e32 v0, v160
	s_waitcnt vmcnt(63) expcnt(7) lgkmcnt(15)
	s_barrier
	s_nop 0
	v_cmp_eq_u32_e32 vcc, 0, v0
	s_and_saveexec_b64 s[2:3], vcc
	v_readlane_b32 s25, v254, 31
	v_readlane_b32 s26, v254, 32
	s_movk_i32 s27, 0x200
	s_movk_i32 s28, 0x300
	s_mov_b64 s[30:31], 0x2000
	s_movk_i32 s34, 0xffa0
	s_cbranch_execz .LBB0_997
	s_getreg_b32 s4, hwreg(HW_REG_XCC_ID, 0, 4)
	v_mov_b32_e32 v0, 0x12100
	s_lshl_b32 s4, s4, 8
	s_waitcnt vmcnt(0) expcnt(0) lgkmcnt(0)
	ds_read_b64 v[0:1], v0
	s_and_b32 s4, s4, 0xf00
	s_mov_b64 s[6:7], exec
	s_add_u32 s4, s76, s4
	s_addc_u32 s5, s77, 0
	v_mbcnt_lo_u32_b32 v2, s6, 0
	s_add_u32 s4, s4, 0x2ac8100
	v_mbcnt_hi_u32_b32 v2, s7, v2
	s_addc_u32 s5, s5, 0
	v_cmp_eq_u32_e32 vcc, 0, v2
	s_and_saveexec_b64 s[8:9], vcc
	s_cbranch_execz .LBB0_963
	s_bcnt1_i32_b64 s6, s[6:7]
	v_mov_b32_e32 v3, s6
	v_mov_b32_e32 v4, 0x1000
	global_atomic_add v3, v4, v3, s[4:5] offset:1024 sc0
